# P6 sample-row mini GEMM: all 8 K-chunks requested before the chunk loop (was one exposed fetch per chunk)
# baseline (speedup 1.0000x reference)
; #define MG_STORE(buf) do { _Pragma("unroll") for (int x_ = 0; x_ < NCH; ++x_) { const int id_ = tid + x_ * NTHREADS, r_ = id_ >> 4, p_ = id_ & 15; \
;         *(LAS u32x4*)(lds + (buf) * BUFB + r_ * 272 + 16 * p_) = pre[x_]; } } while (0)
; template <int MODE>
; __device__ __forceinline__ void mini_gemm(const Args& a, LAS unsigned char* lds, int tid, int wave, int lane, int tile) {
;     ...
;     f32x4 acc[2][NTW];
; #pragma unroll
;     for (int h = 0; h < 2; ++h)
; #pragma unroll
;         for (int n = 0; n < NTW; ++n) acc[h][n] = (f32x4){0.f, 0.f, 0.f, 0.f};
;     __syncthreads();
;     MG_FETCH(0); MG_STORE(0);
;     __syncthreads();
; #pragma unroll 1
;     for (int c = 0; c < 8; ++c) {
;         if (c < 7) MG_FETCH(c + 1);
.LBB0_1167:
	s_lshl_b32 s2, s26, 2
	s_andn2_b32 s2, s2, 63
	s_ashr_i32 s3, s2, 31
	s_lshl_b32 s4, s26, 6
	s_add_u32 s28, s2, 0x4000
	s_addc_u32 s29, s3, 0
	v_mov_b32_e32 v3, s29
	v_or_b32_e32 v2, s28, v52
	s_and_b32 s27, s4, 0x3c0
	v_lshlrev_b64 v[60:61], 10, v[2:3]
	s_sub_i32 s2, s27, 64
	v_lshl_add_u64 v[2:3], v[50:51], 0, v[60:61]
	s_barrier
	global_load_dwordx4 v[18:21], v[2:3], off
	v_or_b32_e32 v34, s28, v54
	v_or_b32_e32 v36, s2, v54
	v_mov_b32_e32 v2, s29
	v_cndmask_b32_e64 v3, 0, v2, s[0:1]
	v_cndmask_b32_e64 v2, v36, v34, s[0:1]
	v_lshlrev_b64 v[2:3], 10, v[2:3]
	v_lshl_add_u64 v[2:3], v[56:57], 0, v[2:3]
	global_load_dwordx4 v[22:25], v[2:3], off
	v_add_u32_e32 v2, s2, v53
	v_mov_b32_e32 v3, v47
	v_lshlrev_b64 v[62:63], 10, v[2:3]
	v_add_u32_e32 v4, s2, v55
	v_mov_b32_e32 v5, v47
	v_lshl_add_u64 v[2:3], v[48:49], 0, v[62:63]
	v_lshlrev_b64 v[64:65], 10, v[4:5]
	v_lshl_add_u64 v[4:5], v[48:49], 0, v[64:65]
	global_load_dwordx4 v[26:29], v[2:3], off
	global_load_dwordx4 v[30:33], v[4:5], off
	v_mov_b32_e32 v4, v47
	v_mov_b32_e32 v5, v47
	v_mov_b32_e32 v37, v47
	v_mov_b32_e32 v2, v47
	v_mov_b32_e32 v3, v47
	v_mov_b64_e32 v[12:13], v[4:5]
	v_mov_b64_e32 v[8:9], v[4:5]
	v_mov_b64_e32 v[16:17], v[4:5]
	v_mov_b32_e32 v35, s29
	s_movk_i32 s30, 0x80
	v_mov_b64_e32 v[10:11], v[2:3]
	v_mov_b64_e32 v[6:7], v[2:3]
	v_mov_b64_e32 v[14:15], v[2:3]
	v_lshlrev_b64 v[66:67], 10, v[34:35]
	v_lshlrev_b64 v[68:69], 10, v[36:37]
	s_mov_b32 s31, 0
	s_add_u32 s2, s10, 0x100
	s_addc_u32 s3, s11, 0
	v_lshl_add_u64 v[250:251], s[2:3], 0, v[46:47]
	s_add_u32 s2, s8, 0x100
	s_addc_u32 s3, s9, 0
	v_lshl_add_u64 v[116:117], s[2:3], 0, v[46:47]
	v_lshl_add_u64 v[254:255], v[116:117], 0, v[60:61]
	global_load_dwordx4 v[84:87], v[254:255], off
	v_lshl_add_u64 v[116:117], v[116:117], 0, v[66:67]
	v_lshl_add_u64 v[246:247], v[250:251], 0, v[68:69]
	v_cndmask_b32_e64 v117, v247, v117, s[0:1]
	v_cndmask_b32_e64 v116, v246, v116, s[0:1]
	global_load_dwordx4 v[88:91], v[116:117], off
	v_lshl_add_u64 v[254:255], v[250:251], 0, v[62:63]
	global_load_dwordx4 v[92:95], v[254:255], off
	v_lshl_add_u64 v[254:255], v[250:251], 0, v[64:65]
	global_load_dwordx4 v[96:99], v[254:255], off
	s_add_u32 s2, s10, 0x200
	s_addc_u32 s3, s11, 0
	v_lshl_add_u64 v[250:251], s[2:3], 0, v[46:47]
	s_add_u32 s2, s8, 0x200
	s_addc_u32 s3, s9, 0
	v_lshl_add_u64 v[116:117], s[2:3], 0, v[46:47]
	v_lshl_add_u64 v[254:255], v[116:117], 0, v[60:61]
	global_load_dwordx4 v[100:103], v[254:255], off
	v_lshl_add_u64 v[116:117], v[116:117], 0, v[66:67]
	v_lshl_add_u64 v[246:247], v[250:251], 0, v[68:69]
	v_cndmask_b32_e64 v117, v247, v117, s[0:1]
	v_cndmask_b32_e64 v116, v246, v116, s[0:1]
	global_load_dwordx4 v[104:107], v[116:117], off
	v_lshl_add_u64 v[254:255], v[250:251], 0, v[62:63]
	global_load_dwordx4 v[108:111], v[254:255], off
	v_lshl_add_u64 v[254:255], v[250:251], 0, v[64:65]
	global_load_dwordx4 v[112:115], v[254:255], off
	s_add_u32 s2, s10, 0x300
	s_addc_u32 s3, s11, 0
	v_lshl_add_u64 v[250:251], s[2:3], 0, v[46:47]
	s_add_u32 s2, s8, 0x300
	s_addc_u32 s3, s9, 0
	v_lshl_add_u64 v[116:117], s[2:3], 0, v[46:47]
	v_lshl_add_u64 v[254:255], v[116:117], 0, v[60:61]
	global_load_dwordx4 v[122:125], v[254:255], off
	v_lshl_add_u64 v[116:117], v[116:117], 0, v[66:67]
	v_lshl_add_u64 v[246:247], v[250:251], 0, v[68:69]
	v_cndmask_b32_e64 v117, v247, v117, s[0:1]
	v_cndmask_b32_e64 v116, v246, v116, s[0:1]
	global_load_dwordx4 v[126:129], v[116:117], off
	v_lshl_add_u64 v[254:255], v[250:251], 0, v[62:63]
	global_load_dwordx4 v[130:133], v[254:255], off
	v_lshl_add_u64 v[254:255], v[250:251], 0, v[64:65]
	global_load_dwordx4 v[134:137], v[254:255], off
	s_add_u32 s2, s43, 0x0
	s_addc_u32 s3, s44, 0
	v_lshl_add_u64 v[250:251], s[2:3], 0, v[46:47]
	s_add_u32 s2, s33, 0x0
	s_addc_u32 s3, s42, 0
	v_lshl_add_u64 v[116:117], s[2:3], 0, v[46:47]
	v_lshl_add_u64 v[254:255], v[116:117], 0, v[60:61]
	global_load_dwordx4 v[138:141], v[254:255], off
	v_lshl_add_u64 v[116:117], v[116:117], 0, v[66:67]
	v_lshl_add_u64 v[246:247], v[250:251], 0, v[68:69]
	v_cndmask_b32_e64 v117, v247, v117, s[0:1]
	v_cndmask_b32_e64 v116, v246, v116, s[0:1]
	global_load_dwordx4 v[142:145], v[116:117], off
	v_lshl_add_u64 v[254:255], v[250:251], 0, v[62:63]
	global_load_dwordx4 v[146:149], v[254:255], off
	v_lshl_add_u64 v[254:255], v[250:251], 0, v[64:65]
	global_load_dwordx4 v[150:153], v[254:255], off
	s_add_u32 s2, s43, 0x100
	s_addc_u32 s3, s44, 0
	v_lshl_add_u64 v[250:251], s[2:3], 0, v[46:47]
	s_add_u32 s2, s33, 0x100
	s_addc_u32 s3, s42, 0
	v_lshl_add_u64 v[116:117], s[2:3], 0, v[46:47]
	v_lshl_add_u64 v[254:255], v[116:117], 0, v[60:61]
	global_load_dwordx4 v[154:157], v[254:255], off
	v_lshl_add_u64 v[116:117], v[116:117], 0, v[66:67]
	v_lshl_add_u64 v[246:247], v[250:251], 0, v[68:69]
	v_cndmask_b32_e64 v117, v247, v117, s[0:1]
	v_cndmask_b32_e64 v116, v246, v116, s[0:1]
	global_load_dwordx4 v[158:161], v[116:117], off
	v_lshl_add_u64 v[254:255], v[250:251], 0, v[62:63]
	global_load_dwordx4 v[162:165], v[254:255], off
	v_lshl_add_u64 v[254:255], v[250:251], 0, v[64:65]
	global_load_dwordx4 v[170:173], v[254:255], off
	s_add_u32 s2, s43, 0x200
	s_addc_u32 s3, s44, 0
	v_lshl_add_u64 v[250:251], s[2:3], 0, v[46:47]
	s_add_u32 s2, s33, 0x200
	s_addc_u32 s3, s42, 0
	v_lshl_add_u64 v[116:117], s[2:3], 0, v[46:47]
	v_lshl_add_u64 v[254:255], v[116:117], 0, v[60:61]
	global_load_dwordx4 v[174:177], v[254:255], off
	v_lshl_add_u64 v[116:117], v[116:117], 0, v[66:67]
	v_lshl_add_u64 v[246:247], v[250:251], 0, v[68:69]
	v_cndmask_b32_e64 v117, v247, v117, s[0:1]
	v_cndmask_b32_e64 v116, v246, v116, s[0:1]
	global_load_dwordx4 v[178:181], v[116:117], off
	v_lshl_add_u64 v[254:255], v[250:251], 0, v[62:63]
	global_load_dwordx4 v[182:185], v[254:255], off
	v_lshl_add_u64 v[254:255], v[250:251], 0, v[64:65]
	global_load_dwordx4 v[186:189], v[254:255], off
	s_add_u32 s2, s43, 0x300
	s_addc_u32 s3, s44, 0
	v_lshl_add_u64 v[250:251], s[2:3], 0, v[46:47]
	s_add_u32 s2, s33, 0x300
	s_addc_u32 s3, s42, 0
	v_lshl_add_u64 v[116:117], s[2:3], 0, v[46:47]
	v_lshl_add_u64 v[254:255], v[116:117], 0, v[60:61]
	global_load_dwordx4 v[190:193], v[254:255], off
	v_lshl_add_u64 v[116:117], v[116:117], 0, v[66:67]
	v_lshl_add_u64 v[246:247], v[250:251], 0, v[68:69]
	v_cndmask_b32_e64 v117, v247, v117, s[0:1]
	v_cndmask_b32_e64 v116, v246, v116, s[0:1]
	global_load_dwordx4 v[194:197], v[116:117], off
	v_lshl_add_u64 v[254:255], v[250:251], 0, v[62:63]
	global_load_dwordx4 v[198:201], v[254:255], off
	v_lshl_add_u64 v[254:255], v[250:251], 0, v[64:65]
	global_load_dwordx4 v[202:205], v[254:255], off
	s_waitcnt vmcnt(31)
	ds_write_b128 v77, v[18:21]
	s_waitcnt vmcnt(30)
	ds_write_b128 v78, v[22:25]
	s_waitcnt vmcnt(29)
	ds_write_b128 v77, v[26:29] offset:17408
	s_waitcnt vmcnt(28)
	ds_write_b128 v79, v[30:33]
	s_waitcnt lgkmcnt(0)
	s_barrier
	s_branch .LBB0_1170
; #define MG_STORE(buf) do { _Pragma("unroll") for (int x_ = 0; x_ < NCH; ++x_) { const int id_ = tid + x_ * NTHREADS, r_ = id_ >> 4, p_ = id_ & 15; \
;         *(LAS u32x4*)(lds + (buf) * BUFB + r_ * 272 + 16 * p_) = pre[x_]; } } while (0)
; template <int MODE>
; __device__ __forceinline__ void mini_gemm(const Args& a, LAS unsigned char* lds, int tid, int wave, int lane, int tile) {
;     ...
;         if (c < 7) MG_STORE((c + 1) & 1);
.LBB0_1168:
	s_andn2_b32 s2, 1, s31
	s_mul_i32 s2, s2, 0x8800
	v_add_u32_e32 v34, s2, v59
	v_add_u32_e32 v35, v34, v72
	v_add_u32_e32 v36, v34, v71
	v_add_u32_e32 v34, v34, v70
	s_cmp_eq_u32 s31, 0
	s_cbranch_scc1 .Lmg0_st_0
	s_cmp_eq_u32 s31, 1
	s_cbranch_scc1 .Lmg0_st_1
	s_cmp_eq_u32 s31, 2
	s_cbranch_scc1 .Lmg0_st_2
	s_cmp_eq_u32 s31, 3
	s_cbranch_scc1 .Lmg0_st_3
	s_cmp_eq_u32 s31, 4
	s_cbranch_scc1 .Lmg0_st_4
	s_cmp_eq_u32 s31, 5
	s_cbranch_scc1 .Lmg0_st_5
	s_waitcnt vmcnt(3)
	ds_write_b128 v34, v[190:193]
	s_waitcnt vmcnt(2)
	ds_write_b128 v36, v[194:197]
	s_waitcnt vmcnt(1)
	ds_write_b128 v34, v[198:201] offset:17408
	s_waitcnt vmcnt(0)
	ds_write_b128 v35, v[202:205]
	s_branch .LBB0_1169
.Lmg0_st_0:
	s_waitcnt vmcnt(27)
	ds_write_b128 v34, v[84:87]
	s_waitcnt vmcnt(26)
	ds_write_b128 v36, v[88:91]
	s_waitcnt vmcnt(25)
	ds_write_b128 v34, v[92:95] offset:17408
	s_waitcnt vmcnt(24)
	ds_write_b128 v35, v[96:99]
	s_branch .LBB0_1169
.Lmg0_st_1:
	s_waitcnt vmcnt(23)
	ds_write_b128 v34, v[100:103]
	s_waitcnt vmcnt(22)
	ds_write_b128 v36, v[104:107]
	s_waitcnt vmcnt(21)
	ds_write_b128 v34, v[108:111] offset:17408
	s_waitcnt vmcnt(20)
	ds_write_b128 v35, v[112:115]
	s_branch .LBB0_1169
.Lmg0_st_2:
	s_waitcnt vmcnt(19)
	ds_write_b128 v34, v[122:125]
	s_waitcnt vmcnt(18)
	ds_write_b128 v36, v[126:129]
	s_waitcnt vmcnt(17)
	ds_write_b128 v34, v[130:133] offset:17408
	s_waitcnt vmcnt(16)
	ds_write_b128 v35, v[134:137]
	s_branch .LBB0_1169
.Lmg0_st_3:
	s_waitcnt vmcnt(15)
	ds_write_b128 v34, v[138:141]
	s_waitcnt vmcnt(14)
	ds_write_b128 v36, v[142:145]
	s_waitcnt vmcnt(13)
	ds_write_b128 v34, v[146:149] offset:17408
	s_waitcnt vmcnt(12)
	ds_write_b128 v35, v[150:153]
	s_branch .LBB0_1169
.Lmg0_st_4:
	s_waitcnt vmcnt(11)
	ds_write_b128 v34, v[154:157]
	s_waitcnt vmcnt(10)
	ds_write_b128 v36, v[158:161]
	s_waitcnt vmcnt(9)
	ds_write_b128 v34, v[162:165] offset:17408
	s_waitcnt vmcnt(8)
	ds_write_b128 v35, v[170:173]
	s_branch .LBB0_1169
.Lmg0_st_5:
	s_waitcnt vmcnt(7)
	ds_write_b128 v34, v[174:177]
	s_waitcnt vmcnt(6)
	ds_write_b128 v36, v[178:181]
	s_waitcnt vmcnt(5)
	ds_write_b128 v34, v[182:185] offset:17408
	s_waitcnt vmcnt(4)
	ds_write_b128 v35, v[186:189]

; #define LAS __attribute__((address_space(3)))
; __device__ __forceinline__ f32x4 mfma16(bf16x8 a, bf16x8 b, f32x4 c) { return __builtin_amdgcn_mfma_f32_16x16x32_bf16(a, b, c, 0, 0, 0); }
; template <int MODE>
; __device__ __forceinline__ void mini_gemm(const Args& a, LAS unsigned char* lds, int tid, int wave, int lane, int tile) {
;     ...
;     for (int c = 0; c < 8; ++c) {
;         if (c < 7) MG_FETCH(c + 1);
;         const LAS unsigned char* B0 = lds + (c & 1) * BUFB;
;         const int hsel = (MODE == 0 && c >= 4) ? 1 : 0;
; #pragma unroll
;         for (int ks = 0; ks < 4; ++ks) {
;             const bf16x8 tf = *(const LAS bf16x8*)(B0 + (16 * rt + i16) * 272 + 64 * ks + 16 * g);
; #pragma unroll
;             for (int n = 0; n < NTW; ++n) {
;                 const bf16x8 wf = *(const LAS bf16x8*)(B0 + (64 + ch * (NC / 2) + 16 * n + i16) * 272 + 64 * ks + 16 * g);
;                 if (hsel) acc[1][n] = mfma16(wf, tf, acc[1][n]); else acc[0][n] = mfma16(wf, tf, acc[0][n]);
.LBB0_1170:
	s_cmp_lg_u32 s31, 7
	s_cselect_b64 s[4:5], -1, 0
.LBB0_1172:
	s_bitcmp1_b32 s31, 0
	s_cselect_b32 s2, 0x8800, 0
	s_add_i32 s2, s2, 0
	v_add_u32_e32 v34, s2, v73
	v_add_u32_e32 v83, v34, v74
	v_add_u32_e32 v34, s2, v74
	v_add_u32_e32 v82, v34, v75
	ds_read_b128 v[34:37], v83
	ds_read_b128 v[38:41], v82
	s_cmp_lt_u32 s31, 4
	s_cselect_b64 s[22:23], -1, 0
	s_mov_b64 s[2:3], -1
	s_and_b64 vcc, exec, s[22:23]
	s_cbranch_vccz .LBB0_1174
	s_mov_b64 s[2:3], 0
	s_waitcnt lgkmcnt(0)
	v_mfma_f32_16x16x32_bf16 v[42:45], v[38:41], v[34:37], v[14:17]
